# P8 DMA issue in MFMA segments + attention loop: 16 dead zero-inits of packed-P registers removed
# baseline (speedup 1.0000x reference)
.LBB0_694:
	ds_read_b128 v[80:83], v196 offset:28672
	ds_read_b128 v[76:79], v194 offset:28672
	ds_read_b128 v[146:149], v194 offset:34816
	ds_read_b128 v[150:153], v196 offset:34816
	ds_read_b128 v[164:167], v198 offset:28672
	ds_read_b128 v[204:207], v198 offset:34816
	ds_read_b128 v[168:171], v199 offset:28672
	ds_read_b128 v[208:211], v199 offset:34816
	ds_read_b128 v[212:215], v201 offset:28672
	ds_read_b128 v[220:223], v201 offset:34816
	s_waitcnt lgkmcnt(8)
	v_mfma_scale_f32_32x32x64_f8f6f4 v[82:97], v[76:83], v[114:121], 0, v1, v1 op_sel_hi:[0,0,0]
	v_exp_f32_e32 v129, v70
	v_exp_f32_e32 v174, v71
	v_exp_f32_e32 v175, v68
	v_exp_f32_e32 v228, v69
	v_exp_f32_e32 v229, v66
	v_exp_f32_e32 v230, v67
	v_exp_f32_e32 v231, v74
	v_exp_f32_e32 v232, v75
	v_exp_f32_e32 v233, v72
	v_exp_f32_e32 v234, v73
	v_exp_f32_e32 v124, v124
	v_exp_f32_e32 v125, v125
	v_exp_f32_e32 v122, v122
	ds_read_b128 v[216:219], v200 offset:28672
	ds_read_b128 v[224:227], v200 offset:34816
	v_exp_f32_e32 v123, v123
	s_waitcnt lgkmcnt(8)
	v_mfma_scale_f32_32x32x64_f8f6f4 v[66:81], v[146:153], v[114:121], 0, v1, v1 op_sel_hi:[0,0,0]
	v_add_f32_e32 v146, 0, v144
	v_add_f32_e32 v146, v145, v146
	v_add_f32_e32 v146, v136, v146
	v_add_f32_e32 v146, v138, v146
	v_add_f32_e32 v146, v142, v146
	v_add_f32_e32 v146, v143, v146
	v_add_f32_e32 v146, v140, v146
	v_add_f32_e32 v146, v141, v146
	v_add_f32_e32 v146, v137, v146
	v_add_f32_e32 v146, v139, v146
	v_add_f32_e32 v146, v130, v146
	v_add_f32_e32 v146, v131, v146
	v_add_f32_e32 v146, v134, v146
	v_add_f32_e32 v146, v135, v146
	v_add_f32_e32 v146, v132, v146
	s_waitcnt lgkmcnt(5)
	v_mfma_scale_f32_32x32x64_f8f6f4 v[82:97], v[164:171], v[106:113], v[82:97], v1, v1 op_sel_hi:[0,0,0]
	v_add_f32_e32 v146, v133, v146
	v_add_f32_e32 v146, v124, v146
	v_add_f32_e32 v146, v125, v146
	v_add_f32_e32 v146, v122, v146
	v_add_f32_e32 v146, v123, v146
	v_add_f32_e32 v146, v129, v146
	v_add_f32_e32 v146, v174, v146
	v_add_f32_e32 v146, v175, v146
	v_add_f32_e32 v146, v228, v146
	v_add_f32_e32 v146, v229, v146
	v_add_f32_e32 v146, v230, v146
	v_exp_f32_e32 v126, v126
	v_add_f32_e32 v146, v231, v146
	v_exp_f32_e32 v127, v127
	v_add_f32_e32 v146, v232, v146
	s_waitcnt lgkmcnt(4)
	v_mfma_scale_f32_32x32x64_f8f6f4 v[66:81], v[204:211], v[106:113], v[66:81], v1, v1 op_sel_hi:[0,0,0]
	v_add_f32_e32 v146, v233, v146
	v_add_f32_e32 v146, v234, v146
	v_add_f32_e32 v146, v126, v146
	v_add_f32_e32 v203, v127, v146
	v_cvt_pk_fp8_f32 v146, v144, v145
	v_cvt_pk_fp8_f32 v150, v124, v125
	v_cvt_pk_fp8_f32 v147, v142, v143
	s_waitcnt lgkmcnt(1)
	v_mfma_scale_f32_32x32x64_f8f6f4 v[82:97], v[212:219], v[98:105], v[82:97], v1, v1 op_sel_hi:[0,0,0]
	v_cvt_pk_fp8_f32 v151, v129, v174
	v_cvt_pk_fp8_f32 v148, v137, v139
	v_cvt_pk_fp8_f32 v152, v229, v230
	v_cvt_pk_fp8_f32 v149, v134, v135
	v_cvt_pk_fp8_f32 v153, v233, v234
	v_mov_b32_e32 v204, v203
	s_nop 1
	v_permlane32_swap_b32_e32 v203, v204
	v_cvt_pk_fp8_f32 v146, v136, v138 op_sel:[0,0,1]
	v_cvt_pk_fp8_f32 v150, v122, v123 op_sel:[0,0,1]
	v_cvt_pk_fp8_f32 v147, v140, v141 op_sel:[0,0,1]
	v_cvt_pk_fp8_f32 v151, v175, v228 op_sel:[0,0,1]
	v_cvt_pk_fp8_f32 v148, v130, v131 op_sel:[0,0,1]
	v_cvt_pk_fp8_f32 v152, v231, v232 op_sel:[0,0,1]
	v_cvt_pk_fp8_f32 v149, v132, v133 op_sel:[0,0,1]
	s_waitcnt lgkmcnt(0)
	v_mfma_scale_f32_32x32x64_f8f6f4 v[66:81], v[220:227], v[98:105], v[66:81], v1, v1 op_sel_hi:[0,0,0]
	v_cvt_pk_fp8_f32 v153, v126, v127 op_sel:[0,0,1]
	s_add_i32 s8, s11, 0xffffe000
	s_add_i32 s9, s72, 0xffffd000
	buffer_load_dwordx4 v[164:167], v191, s[40:43], s8 offen
	buffer_load_dwordx4 v[168:171], v191, s[36:39], s9 offen
	buffer_load_dwordx2 v[174:175], v192, s[36:39], s9 offen
	v_max_f32_e32 v122, v83, v83
	v_max_f32_e32 v123, v82, v82
	v_max_f32_e32 v122, v123, v122
	v_max3_f32 v122, v122, v84, v85
	v_max3_f32 v122, v122, v86, v87
	v_max3_f32 v122, v122, v88, v89
	v_max3_f32 v122, v122, v90, v91
	ds_read_b128 v[130:133], v189
	ds_read_b128 v[134:137], v190
	ds_read_b128 v[138:141], v187 offset:2048
	ds_read_b128 v[206:209], v187 offset:4096
	v_max3_f32 v122, v122, v92, v93
	v_max3_f32 v122, v122, v94, v95
	v_max3_f32 v122, v122, v96, v97
	s_waitcnt lgkmcnt(2)
	v_mfma_scale_f32_32x32x64_f8f6f4 v[2:17], v[146:153], v[130:137], v[2:17], v1, v1 op_sel_hi:[0,0,0]
	ds_read_b128 v[142:145], v186 offset:2048
	ds_read_b128 v[130:133], v187 offset:6144
	ds_read_b128 v[210:213], v186 offset:4096
	ds_read_b128 v[134:137], v186 offset:6144
	v_max3_f32 v122, v122, v66, v67
	v_max3_f32 v122, v122, v68, v69
	v_max3_f32 v122, v122, v70, v71
	v_max3_f32 v122, v122, v72, v73
	v_max3_f32 v122, v122, v74, v75
	v_max3_f32 v122, v122, v76, v77
	v_max3_f32 v122, v122, v78, v79
	v_max3_f32 v122, v122, v80, v81
	v_mov_b32_e32 v123, v122
	s_nop 1
	v_permlane32_swap_b32_e32 v122, v123
	v_max_f32_e32 v123, v123, v123
	v_max_f32_e32 v122, v122, v122
	v_max_f32_e32 v122, v122, v123
	s_waitcnt lgkmcnt(3)
	v_mfma_scale_f32_32x32x64_f8f6f4 v[50:65], v[146:153], v[138:145], v[50:65], v1, v1 op_sel_hi:[0,0,0]
	v_max_f32_e32 v124, v128, v128
	v_sub_f32_e32 v123, v122, v128
	v_max_f32_e32 v122, v124, v122
	v_sub_f32_e32 v124, v128, v122
	v_mul_f32_e32 v124, 0x3dd53b94, v124
	v_exp_f32_e32 v124, v124
	v_cmp_ge_f32_e32 vcc, s61, v123
	s_cmp_eq_u64 vcc, exec
	s_cselect_b64 s[8:9], -1, 0
	s_waitcnt lgkmcnt(0)
	s_barrier
	s_waitcnt vmcnt(3)
	v_cndmask_b32_e64 v205, v124, 1.0, s[8:9]
	v_cmp_gt_f32_e32 vcc, 1.0, v205
	v_mfma_scale_f32_32x32x64_f8f6f4 v[34:49], v[146:153], v[206:213], v[34:49], v1, v1 op_sel_hi:[0,0,0]
	s_waitcnt vmcnt(3)
	ds_write_b128 v193, v[156:159]
	ds_write_b128 v195, v[160:163] offset:16384
	ds_write_b64 v197, v[172:173] offset:16384
	v_mfma_scale_f32_32x32x64_f8f6f4 v[18:33], v[146:153], v[130:137], v[18:33], v1, v1 op_sel_hi:[0,0,0]
	s_cbranch_vccz .LBB0_698
	s_and_saveexec_b64 s[56:57], s[6:7]
	ds_write_b32 v185, v205 offset:41088
	s_or_b64 exec, exec, s[56:57]
	s_waitcnt lgkmcnt(0)
	v_add_u32_e32 v123, v183, v184
	ds_read_b128 v[124:127], v123 offset:41184
	ds_read_b128 v[130:133], v123 offset:41152
	ds_read_b128 v[134:137], v123 offset:41120
	ds_read_b128 v[138:141], v123 offset:41088
	s_waitcnt lgkmcnt(3)
	v_pk_mul_f32 v[14:15], v[14:15], v[124:125]
	s_waitcnt lgkmcnt(2)
	v_pk_mul_f32 v[10:11], v[10:11], v[130:131]
	s_waitcnt lgkmcnt(1)
	v_pk_mul_f32 v[6:7], v[6:7], v[134:135]
	v_pk_mul_f32 v[16:17], v[16:17], v[126:127]
	v_pk_mul_f32 v[12:13], v[12:13], v[132:133]
	v_pk_mul_f32 v[8:9], v[8:9], v[136:137]
	s_waitcnt lgkmcnt(0)
	v_pk_mul_f32 v[4:5], v[4:5], v[140:141]
	v_pk_mul_f32 v[2:3], v[2:3], v[138:139]
	v_pk_mul_f32 v[62:63], v[62:63], v[124:125]
	v_pk_mul_f32 v[58:59], v[58:59], v[130:131]
	v_pk_mul_f32 v[54:55], v[54:55], v[134:135]
	v_pk_mul_f32 v[64:65], v[64:65], v[126:127]
	v_pk_mul_f32 v[60:61], v[60:61], v[132:133]
	v_pk_mul_f32 v[56:57], v[56:57], v[136:137]
	v_pk_mul_f32 v[52:53], v[52:53], v[140:141]
	v_pk_mul_f32 v[50:51], v[50:51], v[138:139]
	v_pk_mul_f32 v[46:47], v[46:47], v[124:125]
	v_pk_mul_f32 v[42:43], v[42:43], v[130:131]
	v_pk_mul_f32 v[38:39], v[38:39], v[134:135]
	v_pk_mul_f32 v[48:49], v[48:49], v[126:127]
	v_pk_mul_f32 v[44:45], v[44:45], v[132:133]
	v_pk_mul_f32 v[40:41], v[40:41], v[136:137]
	v_pk_mul_f32 v[36:37], v[36:37], v[140:141]
	v_pk_mul_f32 v[34:35], v[34:35], v[138:139]
	v_pk_mul_f32 v[30:31], v[30:31], v[124:125]
	v_pk_mul_f32 v[26:27], v[26:27], v[130:131]
	v_pk_mul_f32 v[22:23], v[22:23], v[134:135]
	v_pk_mul_f32 v[32:33], v[32:33], v[126:127]
	v_pk_mul_f32 v[28:29], v[28:29], v[132:133]
	v_pk_mul_f32 v[24:25], v[24:25], v[136:137]
	v_pk_mul_f32 v[20:21], v[20:21], v[140:141]
	v_pk_mul_f32 v[18:19], v[18:19], v[138:139]

.LBB0_700:
	s_waitcnt lgkmcnt(9)
	v_mfma_scale_f32_32x32x64_f8f6f4 v[82:97], v[66:73], v[114:121], 0, v1, v1 op_sel_hi:[0,0,0]
	s_waitcnt lgkmcnt(8)
	v_mfma_scale_f32_32x32x64_f8f6f4 v[66:81], v[74:81], v[114:121], 0, v1, v1 op_sel_hi:[0,0,0]
	s_waitcnt lgkmcnt(5)
	v_mfma_scale_f32_32x32x64_f8f6f4 v[82:97], v[146:153], v[106:113], v[82:97], v1, v1 op_sel_hi:[0,0,0]
	s_waitcnt lgkmcnt(4)
	v_mfma_scale_f32_32x32x64_f8f6f4 v[66:81], v[138:145], v[106:113], v[66:81], v1, v1 op_sel_hi:[0,0,0]
	v_cvt_pk_fp8_f32 v138, v223, v224
	v_cvt_pk_fp8_f32 v142, v239, v240
	v_cvt_pk_fp8_f32 v139, v221, v222
	v_cvt_pk_fp8_f32 v143, v237, v238
	v_cvt_pk_fp8_f32 v140, v216, v218
	v_cvt_pk_fp8_f32 v144, v231, v232
	v_cvt_pk_fp8_f32 v141, v213, v214
	s_waitcnt lgkmcnt(1)
	v_mfma_scale_f32_32x32x64_f8f6f4 v[82:97], v[130:137], v[98:105], v[82:97], v1, v1 op_sel_hi:[0,0,0]
	v_cvt_pk_fp8_f32 v145, v229, v230
	v_cvt_pk_fp8_f32 v138, v215, v217 op_sel:[0,0,1]
	v_cvt_pk_fp8_f32 v142, v233, v234 op_sel:[0,0,1]
	v_cvt_pk_fp8_f32 v139, v219, v220 op_sel:[0,0,1]
	v_cvt_pk_fp8_f32 v143, v235, v236 op_sel:[0,0,1]
	v_cvt_pk_fp8_f32 v140, v209, v210 op_sel:[0,0,1]
	v_cvt_pk_fp8_f32 v144, v225, v226 op_sel:[0,0,1]
	v_cvt_pk_fp8_f32 v141, v211, v212 op_sel:[0,0,1]
	v_cvt_pk_fp8_f32 v145, v227, v228 op_sel:[0,0,1]
	s_waitcnt lgkmcnt(0)
	v_mfma_scale_f32_32x32x64_f8f6f4 v[66:81], v[122:129], v[98:105], v[66:81], v1, v1 op_sel_hi:[0,0,0]
	ds_read_b128 v[122:125], v189 offset:8192
	ds_read_b128 v[126:129], v190 offset:8192
	ds_read_b128 v[130:133], v187 offset:10240
	ds_read_b128 v[146:149], v187 offset:12288
	ds_read_b128 v[134:137], v186 offset:10240
	ds_read_b128 v[210:213], v187 offset:14336
	ds_read_b128 v[150:153], v186 offset:12288
	ds_read_b128 v[214:217], v186 offset:14336
	s_waitcnt lgkmcnt(0)
	v_mfma_scale_f32_32x32x64_f8f6f4 v[2:17], v[138:145], v[122:129], v[2:17], v1, v1 op_sel_hi:[0,0,0]
	v_max_f32_e32 v122, v83, v83
	v_max_f32_e32 v123, v82, v82
	v_max_f32_e32 v122, v123, v122
	v_max3_f32 v122, v122, v84, v85
	v_max3_f32 v122, v122, v86, v87
	v_max3_f32 v122, v122, v88, v89
	v_max3_f32 v122, v122, v90, v91
	v_max3_f32 v122, v122, v92, v93
	v_max3_f32 v122, v122, v94, v95
	v_max3_f32 v122, v122, v96, v97
	v_max3_f32 v122, v122, v66, v67
	v_max3_f32 v122, v122, v68, v69
	v_max3_f32 v122, v122, v70, v71
	v_max3_f32 v122, v122, v72, v73
	v_max3_f32 v122, v122, v74, v75
	v_mfma_scale_f32_32x32x64_f8f6f4 v[50:65], v[138:145], v[130:137], v[50:65], v1, v1 op_sel_hi:[0,0,0]
	v_max3_f32 v122, v122, v76, v77
	v_max3_f32 v122, v122, v78, v79
	v_max3_f32 v122, v122, v80, v81
	v_mov_b32_e32 v123, v122
	s_nop 1
	v_permlane32_swap_b32_e32 v122, v123
	v_max_f32_e32 v123, v123, v123
	v_max_f32_e32 v122, v122, v122
	v_max_f32_e32 v122, v122, v123
	v_max_f32_e32 v124, v206, v206
	v_sub_f32_e32 v123, v122, v206
	v_max_f32_e32 v122, v124, v122
	v_sub_f32_e32 v124, v206, v122
	v_mul_f32_e32 v124, 0x3dd53b94, v124
	v_exp_f32_e32 v124, v124
	v_mfma_scale_f32_32x32x64_f8f6f4 v[34:49], v[138:145], v[146:153], v[34:49], v1, v1 op_sel_hi:[0,0,0]
	v_cmp_ge_f32_e32 vcc, s61, v123
	s_cmp_eq_u64 vcc, exec
	s_cselect_b64 s[8:9], -1, 0
	s_barrier
	s_waitcnt vmcnt(3)
	v_cndmask_b32_e64 v129, v124, 1.0, s[8:9]
	v_cmp_gt_f32_e32 vcc, 1.0, v129
	s_waitcnt vmcnt(2)
	ds_write_b128 v193, v[164:167] offset:8192
	s_waitcnt vmcnt(1)
	ds_write_b128 v195, v[168:171] offset:28672
	s_waitcnt vmcnt(0)
	ds_write_b64 v197, v[174:175] offset:28672
	v_mfma_scale_f32_32x32x64_f8f6f4 v[18:33], v[138:145], v[210:217], v[18:33], v1, v1 op_sel_hi:[0,0,0]
	s_cbranch_vccz .LBB0_704
	s_and_saveexec_b64 s[58:59], s[6:7]
	ds_write_b32 v185, v129 offset:41088
	s_or_b64 exec, exec, s[58:59]
	s_waitcnt lgkmcnt(0)
	v_add_u32_e32 v123, v183, v184
	ds_read_b128 v[124:127], v123 offset:41184
	ds_read_b128 v[130:133], v123 offset:41152
	ds_read_b128 v[134:137], v123 offset:41120
	ds_read_b128 v[138:141], v123 offset:41088
	s_waitcnt lgkmcnt(3)
	v_pk_mul_f32 v[14:15], v[14:15], v[124:125]
	s_waitcnt lgkmcnt(2)
	v_pk_mul_f32 v[10:11], v[10:11], v[130:131]
	s_waitcnt lgkmcnt(1)
	v_pk_mul_f32 v[6:7], v[6:7], v[134:135]
	v_pk_mul_f32 v[16:17], v[16:17], v[126:127]
	v_pk_mul_f32 v[12:13], v[12:13], v[132:133]
	v_pk_mul_f32 v[8:9], v[8:9], v[136:137]
	s_waitcnt lgkmcnt(0)
	v_pk_mul_f32 v[4:5], v[4:5], v[140:141]
	v_pk_mul_f32 v[2:3], v[2:3], v[138:139]
	v_pk_mul_f32 v[62:63], v[62:63], v[124:125]
	v_pk_mul_f32 v[58:59], v[58:59], v[130:131]
	v_pk_mul_f32 v[54:55], v[54:55], v[134:135]
	v_pk_mul_f32 v[64:65], v[64:65], v[126:127]
	v_pk_mul_f32 v[60:61], v[60:61], v[132:133]
	v_pk_mul_f32 v[56:57], v[56:57], v[136:137]
	v_pk_mul_f32 v[52:53], v[52:53], v[140:141]
	v_pk_mul_f32 v[50:51], v[50:51], v[138:139]
	v_pk_mul_f32 v[46:47], v[46:47], v[124:125]
	v_pk_mul_f32 v[42:43], v[42:43], v[130:131]
	v_pk_mul_f32 v[38:39], v[38:39], v[134:135]
	v_pk_mul_f32 v[48:49], v[48:49], v[126:127]
	v_pk_mul_f32 v[44:45], v[44:45], v[132:133]
	v_pk_mul_f32 v[40:41], v[40:41], v[136:137]
	v_pk_mul_f32 v[36:37], v[36:37], v[140:141]
	v_pk_mul_f32 v[34:35], v[34:35], v[138:139]
	v_pk_mul_f32 v[30:31], v[30:31], v[124:125]
	v_pk_mul_f32 v[26:27], v[26:27], v[130:131]
	v_pk_mul_f32 v[22:23], v[22:23], v[134:135]
	v_pk_mul_f32 v[32:33], v[32:33], v[126:127]
	v_pk_mul_f32 v[28:29], v[28:29], v[132:133]
	v_pk_mul_f32 v[24:25], v[24:25], v[136:137]
	v_pk_mul_f32 v[20:21], v[20:21], v[140:141]
	v_pk_mul_f32 v[18:19], v[18:19], v[138:139]
